# W_out epilogue: second base load of every row-group pair issued with the first (spare quad), one wait per pair instead of two
# baseline (speedup 1.0000x reference)
; __device__ __forceinline__ unsigned cvt_pk_bf16(float lo, float hi) { f32x2_t v = {lo, hi}; bf16x2_t b = __builtin_convertvector(v, bf16x2_t); return __builtin_bit_cast(unsigned, b); }
;     __device__ __forceinline__ void operator()(const f32x4 (&acc)[2][2][4][2], const Unit& u, int wr, int wc, int fr, int fq) const {
;     ...
;             for (int m = 0; m < 4; ++m) {
;                 const int row = u.pm * BM + ai * HALF + wr * 64 + m * 16 + fr; float ss = 0.f; const float bsc = brow ? brow[row] : 1.0f;
; #pragma unroll
;                 for (int bj = 0; bj < 2; ++bj) { const size_t off = (size_t)row * 1024 + col0 + bj * HALF;
;                     f32x4 b0, b1;
;                     if (basef) { b0 = *(const f32x4*)(basef + off); b1 = *(const f32x4*)(basef + off + 4); }
;                     else { const u32x4 r = *(const u32x4*)(baseh + off);
;                         b0 = (f32x4){__uint_as_float(r.x << 16), __uint_as_float(r.x & 0xffff0000u), __uint_as_float(r.y << 16), __uint_as_float(r.y & 0xffff0000u)} * bsc;
;                         b1 = (f32x4){__uint_as_float(r.z << 16), __uint_as_float(r.z & 0xffff0000u), __uint_as_float(r.w << 16), __uint_as_float(r.w & 0xffff0000u)} * bsc; }
;                     const f32x4 o0 = b0 + acc[ai][bj][m][0] * scale, o1 = b1 + acc[ai][bj][m][1] * scale;
;                     if (out) { __builtin_nontemporal_store(o0, (f32x4*)(out + off)); __builtin_nontemporal_store(o1, (f32x4*)(out + off + 4)); }
;                     if (hb) { u32x4 w; w.x = cvt_pk_bf16(o0[0], o0[1]); w.y = cvt_pk_bf16(o0[2], o0[3]); w.z = cvt_pk_bf16(o1[0], o1[1]); w.w = cvt_pk_bf16(o1[2], o1[3]); *(u32x4*)(hb + off) = w;
;                         ss += ((o0[0] * o0[0] + o0[1] * o0[1]) + (o0[2] * o0[2] + o0[3] * o0[3])) + ((o1[0] * o1[0] + o1[1] * o1[1]) + (o1[2] * o1[2] + o1[3] * o1[3])); } }
;                 if (hb) { ss += __shfl_xor(ss, 16); ss += __shfl_xor(ss, 32); if (fq == 0) atomicAdd(rowss + row, ss); }
.LBB0_1016:
	v_lshl_add_u32 v146, s22, 8, v148
	v_lshl_or_b32 v144, s24, 8, v150
	v_ashrrev_i32_e32 v147, 31, v146
	v_ashrrev_i32_e32 v145, 31, v144
	v_lshlrev_b64 v[156:157], 10, v[146:147]
	v_lshl_add_u64 v[156:157], v[156:157], 0, v[144:145]
	v_lshlrev_b64 v[160:161], 1, v[156:157]
	v_lshl_add_u64 v[162:163], s[84:85], 0, v[160:161]
	global_load_dwordx4 v[156:159], v[162:163], off
	v_lshl_add_u64 v[164:165], s[8:9], 0, v[160:161]
	v_xor_b32_e32 v155, 32, v154
	v_or_b32_e32 v160, 0x100, v160
	global_load_dwordx4 v[228:231], v[162:163], off offset:256
	s_waitcnt vmcnt(0)
	v_lshlrev_b32_e32 v166, 16, v156
	v_and_b32_e32 v167, 0xffff0000, v156
	v_lshlrev_b32_e32 v156, 16, v157
	v_and_b32_e32 v157, 0xffff0000, v157
	v_lshlrev_b32_e32 v168, 16, v158
	v_and_b32_e32 v169, 0xffff0000, v158
	v_lshlrev_b32_e32 v158, 16, v159
	v_and_b32_e32 v159, 0xffff0000, v159
	v_pk_add_f32 v[126:127], v[126:127], v[156:157]
	v_pk_add_f32 v[156:157], v[124:125], v[166:167]
	v_pk_add_f32 v[158:159], v[122:123], v[158:159]
	v_pk_add_f32 v[166:167], v[120:121], v[168:169]
	v_cvt_pk_bf16_f32 v120, v156, v157
	v_cvt_pk_bf16_f32 v121, v126, v127
	v_cvt_pk_bf16_f32 v122, v166, v167
	v_cvt_pk_bf16_f32 v123, v158, v159
	global_store_dwordx4 v[164:165], v[120:123], off
	s_nop 1
	v_mul_f32_e32 v157, v157, v157
	v_mul_f32_e32 v127, v127, v127
	v_mul_f32_e32 v162, v167, v167
	v_mul_f32_e32 v159, v159, v159
	v_fmac_f32_e32 v157, v156, v156
	v_fmac_f32_e32 v127, v126, v126
	v_fmac_f32_e32 v162, v166, v166
	v_fmac_f32_e32 v159, v158, v158
	v_add_f32_e32 v126, v157, v127
	v_add_f32_e32 v127, v162, v159
	v_add_f32_e32 v158, v126, v127
	v_and_b32_e32 v121, 64, v154
	v_xor_b32_e32 v120, 16, v154
	v_add_u32_e32 v121, 64, v121
	v_cmp_lt_i32_e32 vcc, v120, v121
	s_nop 0
	v_lshlrev_b32_e32 v126, 16, v228
	v_and_b32_e32 v127, 0xffff0000, v228
	v_lshlrev_b32_e32 v122, 16, v229
	v_and_b32_e32 v123, 0xffff0000, v229
	v_lshlrev_b32_e32 v156, 16, v230
	v_and_b32_e32 v157, 0xffff0000, v230
	v_lshlrev_b32_e32 v124, 16, v231
	v_and_b32_e32 v125, 0xffff0000, v231
	v_pk_add_f32 v[118:119], v[118:119], v[122:123]
	v_pk_add_f32 v[116:117], v[116:117], v[126:127]
	v_pk_add_f32 v[122:123], v[114:115], v[124:125]
	v_pk_add_f32 v[112:113], v[112:113], v[156:157]
	v_mul_f32_e32 v114, v117, v117
	v_mul_f32_e32 v115, v119, v119
	v_mul_f32_e32 v124, v113, v113
	v_mul_f32_e32 v125, v123, v123
	v_fmac_f32_e32 v114, v116, v116
	v_fmac_f32_e32 v115, v118, v118
	v_fmac_f32_e32 v124, v112, v112
	v_fmac_f32_e32 v125, v122, v122
	v_add_f32_e32 v114, v114, v115
	v_add_f32_e32 v115, v124, v125
	v_cndmask_b32_e32 v120, v154, v120, vcc
	v_add_f32_e32 v114, v114, v115
	v_lshlrev_b32_e32 v120, 2, v120
	v_add_f32_e32 v114, v158, v114
	ds_bpermute_b32 v115, v120, v114
	v_cmp_lt_i32_e32 vcc, v155, v121
	v_cvt_pk_bf16_f32 v116, v116, v117
	v_cvt_pk_bf16_f32 v117, v118, v119
	v_cndmask_b32_e32 v121, v154, v155, vcc
	v_cvt_pk_bf16_f32 v118, v112, v113
	s_waitcnt lgkmcnt(0)
	v_add_f32_e32 v112, v114, v115
	v_lshlrev_b32_e32 v114, 2, v121
	ds_bpermute_b32 v113, v114, v112
	v_cvt_pk_bf16_f32 v119, v122, v123
	v_lshl_add_u64 v[122:123], s[8:9], 0, v[160:161]
	global_store_dwordx4 v[122:123], v[116:119], off
	s_and_saveexec_b64 s[22:23], s[2:3]
	s_cbranch_execz .LBB0_1018
	v_lshl_add_u64 v[116:117], v[146:147], 2, s[0:1]
	s_waitcnt lgkmcnt(0)
	v_add_f32_e32 v112, v112, v113
	global_atomic_add_f32 v[116:117], v112, off
.LBB0_1018:
	s_or_b64 exec, exec, s[22:23]
	v_or_b32_e32 v112, 16, v146
	s_waitcnt lgkmcnt(0)
	v_ashrrev_i32_e32 v113, 31, v112
	v_lshlrev_b64 v[116:117], 10, v[112:113]
	v_lshl_add_u64 v[116:117], v[116:117], 0, v[144:145]
	v_lshlrev_b64 v[122:123], 1, v[116:117]
	v_lshl_add_u64 v[124:125], s[84:85], 0, v[122:123]
	global_load_dwordx4 v[116:119], v[124:125], off
	v_lshl_add_u64 v[126:127], s[8:9], 0, v[122:123]
	v_or_b32_e32 v122, 0x100, v122
	global_load_dwordx4 v[232:235], v[124:125], off offset:256
	s_waitcnt vmcnt(0)
	v_lshlrev_b32_e32 v156, 16, v116
	v_and_b32_e32 v157, 0xffff0000, v116
	v_lshlrev_b32_e32 v116, 16, v117
	v_and_b32_e32 v117, 0xffff0000, v117
	v_lshlrev_b32_e32 v158, 16, v118
	v_and_b32_e32 v159, 0xffff0000, v118
	v_lshlrev_b32_e32 v118, 16, v119
	v_and_b32_e32 v119, 0xffff0000, v119
	v_pk_add_f32 v[110:111], v[110:111], v[116:117]
	v_pk_add_f32 v[108:109], v[108:109], v[156:157]
	v_pk_add_f32 v[116:117], v[106:107], v[118:119]
	v_pk_add_f32 v[118:119], v[104:105], v[158:159]
	v_cvt_pk_bf16_f32 v104, v108, v109
	v_cvt_pk_bf16_f32 v105, v110, v111
	v_cvt_pk_bf16_f32 v106, v118, v119
	v_cvt_pk_bf16_f32 v107, v116, v117
	global_store_dwordx4 v[126:127], v[104:107], off
	s_nop 1
	v_mul_f32_e32 v109, v109, v109
	v_mul_f32_e32 v111, v111, v111
	v_mul_f32_e32 v115, v119, v119
	v_mul_f32_e32 v117, v117, v117
	v_fmac_f32_e32 v109, v108, v108
	v_fmac_f32_e32 v111, v110, v110
	v_fmac_f32_e32 v115, v118, v118
	v_fmac_f32_e32 v117, v116, v116
	v_add_f32_e32 v108, v109, v111
	v_add_f32_e32 v109, v115, v117
	v_add_f32_e32 v115, v108, v109
	s_nop 0
	v_lshlrev_b32_e32 v108, 16, v232
	v_and_b32_e32 v109, 0xffff0000, v232
	v_lshlrev_b32_e32 v104, 16, v233
	v_and_b32_e32 v105, 0xffff0000, v233
	v_lshlrev_b32_e32 v110, 16, v234
	v_and_b32_e32 v111, 0xffff0000, v234
	v_lshlrev_b32_e32 v106, 16, v235
	v_and_b32_e32 v107, 0xffff0000, v235
	v_pk_add_f32 v[102:103], v[102:103], v[104:105]
	v_pk_add_f32 v[100:101], v[100:101], v[108:109]
	v_pk_add_f32 v[104:105], v[98:99], v[106:107]
	v_pk_add_f32 v[96:97], v[96:97], v[110:111]
	v_mul_f32_e32 v98, v101, v101
	v_mul_f32_e32 v99, v103, v103
	v_mul_f32_e32 v106, v97, v97
	v_mul_f32_e32 v107, v105, v105
	v_fmac_f32_e32 v98, v100, v100
	v_fmac_f32_e32 v99, v102, v102
	v_fmac_f32_e32 v106, v96, v96
	v_fmac_f32_e32 v107, v104, v104
	v_add_f32_e32 v98, v98, v99
	v_add_f32_e32 v99, v106, v107
	v_add_f32_e32 v98, v98, v99
	v_add_f32_e32 v106, v115, v98
	ds_bpermute_b32 v107, v120, v106
	v_cvt_pk_bf16_f32 v98, v100, v101
	v_cvt_pk_bf16_f32 v100, v96, v97
	v_cvt_pk_bf16_f32 v99, v102, v103
	v_cvt_pk_bf16_f32 v101, v104, v105
	s_waitcnt lgkmcnt(0)
	v_add_f32_e32 v96, v106, v107
	ds_bpermute_b32 v97, v114, v96
	v_lshl_add_u64 v[102:103], s[8:9], 0, v[122:123]
	global_store_dwordx4 v[102:103], v[98:101], off
	s_and_saveexec_b64 s[22:23], s[2:3]
	s_cbranch_execz .LBB0_1020
	v_lshl_add_u64 v[98:99], v[112:113], 2, s[0:1]
	s_waitcnt lgkmcnt(0)
	v_add_f32_e32 v96, v96, v97
	global_atomic_add_f32 v[98:99], v96, off
; __device__ __forceinline__ unsigned cvt_pk_bf16(float lo, float hi) { f32x2_t v = {lo, hi}; bf16x2_t b = __builtin_convertvector(v, bf16x2_t); return __builtin_bit_cast(unsigned, b); }
;     __device__ __forceinline__ void operator()(const f32x4 (&acc)[2][2][4][2], const Unit& u, int wr, int wc, int fr, int fq) const {
;     ...
;             for (int m = 0; m < 4; ++m) {
;                 const int row = u.pm * BM + ai * HALF + wr * 64 + m * 16 + fr; float ss = 0.f; const float bsc = brow ? brow[row] : 1.0f;
; #pragma unroll
;                 for (int bj = 0; bj < 2; ++bj) { const size_t off = (size_t)row * 1024 + col0 + bj * HALF;
;                     f32x4 b0, b1;
;                     if (basef) { b0 = *(const f32x4*)(basef + off); b1 = *(const f32x4*)(basef + off + 4); }
;                     else { const u32x4 r = *(const u32x4*)(baseh + off);
;                         b0 = (f32x4){__uint_as_float(r.x << 16), __uint_as_float(r.x & 0xffff0000u), __uint_as_float(r.y << 16), __uint_as_float(r.y & 0xffff0000u)} * bsc;
;                         b1 = (f32x4){__uint_as_float(r.z << 16), __uint_as_float(r.z & 0xffff0000u), __uint_as_float(r.w << 16), __uint_as_float(r.w & 0xffff0000u)} * bsc; }
;                     const f32x4 o0 = b0 + acc[ai][bj][m][0] * scale, o1 = b1 + acc[ai][bj][m][1] * scale;
;                     if (out) { __builtin_nontemporal_store(o0, (f32x4*)(out + off)); __builtin_nontemporal_store(o1, (f32x4*)(out + off + 4)); }
;                     if (hb) { u32x4 w; w.x = cvt_pk_bf16(o0[0], o0[1]); w.y = cvt_pk_bf16(o0[2], o0[3]); w.z = cvt_pk_bf16(o1[0], o1[1]); w.w = cvt_pk_bf16(o1[2], o1[3]); *(u32x4*)(hb + off) = w;
;                         ss += ((o0[0] * o0[0] + o0[1] * o0[1]) + (o0[2] * o0[2] + o0[3] * o0[3])) + ((o1[0] * o1[0] + o1[1] * o1[1]) + (o1[2] * o1[2] + o1[3] * o1[3])); } }
;                 if (hb) { ss += __shfl_xor(ss, 16); ss += __shfl_xor(ss, 32); if (fq == 0) atomicAdd(rowss + row, ss); }
.LBB0_1020:
	s_or_b64 exec, exec, s[22:23]
	v_or_b32_e32 v96, 32, v146
	s_waitcnt lgkmcnt(0)
	v_ashrrev_i32_e32 v97, 31, v96
	v_lshlrev_b64 v[98:99], 10, v[96:97]
	v_lshl_add_u64 v[98:99], v[98:99], 0, v[144:145]
	v_lshlrev_b64 v[102:103], 1, v[98:99]
	v_lshl_add_u64 v[104:105], s[84:85], 0, v[102:103]
	global_load_dwordx4 v[98:101], v[104:105], off
	v_lshl_add_u64 v[106:107], s[8:9], 0, v[102:103]
	v_or_b32_e32 v102, 0x100, v102
	global_load_dwordx4 v[228:231], v[104:105], off offset:256
	s_waitcnt vmcnt(0)
	v_lshlrev_b32_e32 v108, 16, v98
	v_and_b32_e32 v109, 0xffff0000, v98
	v_lshlrev_b32_e32 v98, 16, v99
	v_and_b32_e32 v99, 0xffff0000, v99
	v_lshlrev_b32_e32 v110, 16, v100
	v_and_b32_e32 v111, 0xffff0000, v100
	v_lshlrev_b32_e32 v100, 16, v101
	v_and_b32_e32 v101, 0xffff0000, v101
	v_pk_add_f32 v[94:95], v[94:95], v[98:99]
	v_pk_add_f32 v[92:93], v[92:93], v[108:109]
	v_pk_add_f32 v[98:99], v[90:91], v[100:101]
	v_pk_add_f32 v[100:101], v[88:89], v[110:111]
	v_cvt_pk_bf16_f32 v88, v92, v93
	v_cvt_pk_bf16_f32 v89, v94, v95
	v_cvt_pk_bf16_f32 v90, v100, v101
	v_cvt_pk_bf16_f32 v91, v98, v99
	global_store_dwordx4 v[106:107], v[88:91], off
	s_nop 1
	v_mul_f32_e32 v93, v93, v93
	v_mul_f32_e32 v95, v95, v95
	v_mul_f32_e32 v101, v101, v101
	v_mul_f32_e32 v99, v99, v99
	v_fmac_f32_e32 v93, v92, v92
	v_fmac_f32_e32 v95, v94, v94
	v_fmac_f32_e32 v101, v100, v100
	v_fmac_f32_e32 v99, v98, v98
	v_add_f32_e32 v92, v93, v95
	v_add_f32_e32 v93, v101, v99
	v_add_f32_e32 v98, v92, v93
	s_nop 0
	v_lshlrev_b32_e32 v92, 16, v228
	v_and_b32_e32 v93, 0xffff0000, v228
	v_lshlrev_b32_e32 v88, 16, v229
	v_and_b32_e32 v89, 0xffff0000, v229
	v_lshlrev_b32_e32 v94, 16, v230
	v_and_b32_e32 v95, 0xffff0000, v230
	v_lshlrev_b32_e32 v90, 16, v231
	v_and_b32_e32 v91, 0xffff0000, v231
	v_pk_add_f32 v[86:87], v[86:87], v[88:89]
	v_pk_add_f32 v[84:85], v[84:85], v[92:93]
	v_pk_add_f32 v[88:89], v[82:83], v[90:91]
	v_pk_add_f32 v[80:81], v[80:81], v[94:95]
	v_mul_f32_e32 v82, v85, v85
	v_mul_f32_e32 v83, v87, v87
	v_mul_f32_e32 v90, v81, v81
	v_mul_f32_e32 v91, v89, v89
	v_fmac_f32_e32 v82, v84, v84
	v_fmac_f32_e32 v83, v86, v86
	v_fmac_f32_e32 v90, v80, v80
	v_fmac_f32_e32 v91, v88, v88
	v_add_f32_e32 v82, v82, v83
	v_add_f32_e32 v83, v90, v91
	v_add_f32_e32 v82, v82, v83
	v_add_f32_e32 v90, v98, v82
	ds_bpermute_b32 v91, v120, v90
	v_cvt_pk_bf16_f32 v82, v84, v85
	v_cvt_pk_bf16_f32 v84, v80, v81
	v_cvt_pk_bf16_f32 v83, v86, v87
	v_cvt_pk_bf16_f32 v85, v88, v89
	s_waitcnt lgkmcnt(0)
	v_add_f32_e32 v80, v90, v91
	ds_bpermute_b32 v81, v114, v80
	v_lshl_add_u64 v[86:87], s[8:9], 0, v[102:103]
	global_store_dwordx4 v[86:87], v[82:85], off
	s_and_saveexec_b64 s[22:23], s[2:3]
	s_cbranch_execz .LBB0_1022
	v_lshl_add_u64 v[82:83], v[96:97], 2, s[0:1]
	s_waitcnt lgkmcnt(0)
	v_add_f32_e32 v80, v80, v81
	global_atomic_add_f32 v[82:83], v80, off
.LBB0_1022:
	s_or_b64 exec, exec, s[22:23]
	v_or_b32_e32 v80, 48, v146
	s_waitcnt lgkmcnt(0)
	v_ashrrev_i32_e32 v81, 31, v80
	v_lshlrev_b64 v[82:83], 10, v[80:81]
	v_lshl_add_u64 v[82:83], v[82:83], 0, v[144:145]
	v_lshlrev_b64 v[86:87], 1, v[82:83]
	v_lshl_add_u64 v[88:89], s[84:85], 0, v[86:87]
	global_load_dwordx4 v[82:85], v[88:89], off
	v_lshl_add_u64 v[90:91], s[8:9], 0, v[86:87]
	v_or_b32_e32 v86, 0x100, v86
	global_load_dwordx4 v[232:235], v[88:89], off offset:256
	s_waitcnt vmcnt(0)
	v_lshlrev_b32_e32 v92, 16, v82
	v_and_b32_e32 v93, 0xffff0000, v82
	v_lshlrev_b32_e32 v82, 16, v83
	v_and_b32_e32 v83, 0xffff0000, v83
	v_lshlrev_b32_e32 v94, 16, v84
	v_and_b32_e32 v95, 0xffff0000, v84
	v_lshlrev_b32_e32 v84, 16, v85
	v_and_b32_e32 v85, 0xffff0000, v85
	v_pk_add_f32 v[78:79], v[78:79], v[82:83]
	v_pk_add_f32 v[76:77], v[76:77], v[92:93]
	v_pk_add_f32 v[82:83], v[74:75], v[84:85]
	v_pk_add_f32 v[84:85], v[72:73], v[94:95]
	v_cvt_pk_bf16_f32 v72, v76, v77
	v_cvt_pk_bf16_f32 v73, v78, v79
	v_cvt_pk_bf16_f32 v74, v84, v85
	v_cvt_pk_bf16_f32 v75, v82, v83
	global_store_dwordx4 v[90:91], v[72:75], off
	s_nop 1
	v_mul_f32_e32 v77, v77, v77
	v_mul_f32_e32 v79, v79, v79
	v_mul_f32_e32 v85, v85, v85
	v_mul_f32_e32 v83, v83, v83
	v_fmac_f32_e32 v77, v76, v76
	v_fmac_f32_e32 v79, v78, v78
	v_fmac_f32_e32 v85, v84, v84
	v_fmac_f32_e32 v83, v82, v82
	v_add_f32_e32 v76, v77, v79
	v_add_f32_e32 v77, v85, v83
	v_add_f32_e32 v82, v76, v77
	s_nop 0
	v_lshlrev_b32_e32 v76, 16, v232
	v_and_b32_e32 v77, 0xffff0000, v232
	v_lshlrev_b32_e32 v72, 16, v233
	v_and_b32_e32 v73, 0xffff0000, v233
	v_lshlrev_b32_e32 v78, 16, v234
	v_and_b32_e32 v79, 0xffff0000, v234
	v_lshlrev_b32_e32 v74, 16, v235
	v_and_b32_e32 v75, 0xffff0000, v235
	v_pk_add_f32 v[70:71], v[70:71], v[72:73]
	v_pk_add_f32 v[68:69], v[68:69], v[76:77]
	v_pk_add_f32 v[72:73], v[66:67], v[74:75]
	v_pk_add_f32 v[64:65], v[64:65], v[78:79]
	v_mul_f32_e32 v66, v69, v69
	v_mul_f32_e32 v67, v71, v71
	v_mul_f32_e32 v74, v65, v65
	v_mul_f32_e32 v75, v73, v73
	v_fmac_f32_e32 v66, v68, v68
	v_fmac_f32_e32 v67, v70, v70
	v_fmac_f32_e32 v74, v64, v64
	v_fmac_f32_e32 v75, v72, v72
	v_add_f32_e32 v66, v66, v67
	v_add_f32_e32 v67, v74, v75
	v_add_f32_e32 v66, v66, v67
	v_add_f32_e32 v74, v82, v66
	ds_bpermute_b32 v75, v120, v74
	v_cvt_pk_bf16_f32 v66, v68, v69
	v_cvt_pk_bf16_f32 v68, v64, v65
	v_cvt_pk_bf16_f32 v67, v70, v71
	v_cvt_pk_bf16_f32 v69, v72, v73
	s_waitcnt lgkmcnt(0)
	v_add_f32_e32 v64, v74, v75
	ds_bpermute_b32 v65, v114, v64
	v_lshl_add_u64 v[70:71], s[8:9], 0, v[86:87]
	global_store_dwordx4 v[70:71], v[66:69], off
	s_and_saveexec_b64 s[22:23], s[2:3]
	s_cbranch_execz .LBB0_1024
	v_lshl_add_u64 v[66:67], v[80:81], 2, s[0:1]
	s_waitcnt lgkmcnt(0)
	v_add_f32_e32 v64, v64, v65
	global_atomic_add_f32 v[66:67], v64, off
; __device__ __forceinline__ unsigned cvt_pk_bf16(float lo, float hi) { f32x2_t v = {lo, hi}; bf16x2_t b = __builtin_convertvector(v, bf16x2_t); return __builtin_bit_cast(unsigned, b); }
;     __device__ __forceinline__ void operator()(const f32x4 (&acc)[2][2][4][2], const Unit& u, int wr, int wc, int fr, int fq) const {
;     ...
;             for (int m = 0; m < 4; ++m) {
;                 const int row = u.pm * BM + ai * HALF + wr * 64 + m * 16 + fr; float ss = 0.f; const float bsc = brow ? brow[row] : 1.0f;
; #pragma unroll
;                 for (int bj = 0; bj < 2; ++bj) { const size_t off = (size_t)row * 1024 + col0 + bj * HALF;
;                     f32x4 b0, b1;
;                     if (basef) { b0 = *(const f32x4*)(basef + off); b1 = *(const f32x4*)(basef + off + 4); }
;                     else { const u32x4 r = *(const u32x4*)(baseh + off);
;                         b0 = (f32x4){__uint_as_float(r.x << 16), __uint_as_float(r.x & 0xffff0000u), __uint_as_float(r.y << 16), __uint_as_float(r.y & 0xffff0000u)} * bsc;
;                         b1 = (f32x4){__uint_as_float(r.z << 16), __uint_as_float(r.z & 0xffff0000u), __uint_as_float(r.w << 16), __uint_as_float(r.w & 0xffff0000u)} * bsc; }
;                     const f32x4 o0 = b0 + acc[ai][bj][m][0] * scale, o1 = b1 + acc[ai][bj][m][1] * scale;
;                     if (out) { __builtin_nontemporal_store(o0, (f32x4*)(out + off)); __builtin_nontemporal_store(o1, (f32x4*)(out + off + 4)); }
;                     if (hb) { u32x4 w; w.x = cvt_pk_bf16(o0[0], o0[1]); w.y = cvt_pk_bf16(o0[2], o0[3]); w.z = cvt_pk_bf16(o1[0], o1[1]); w.w = cvt_pk_bf16(o1[2], o1[3]); *(u32x4*)(hb + off) = w;
;                         ss += ((o0[0] * o0[0] + o0[1] * o0[1]) + (o0[2] * o0[2] + o0[3] * o0[3])) + ((o1[0] * o1[0] + o1[1] * o1[1]) + (o1[2] * o1[2] + o1[3] * o1[3])); } }
;                 if (hb) { ss += __shfl_xor(ss, 16); ss += __shfl_xor(ss, 32); if (fq == 0) atomicAdd(rowss + row, ss); }
.LBB0_1024:
	s_or_b64 exec, exec, s[22:23]
	v_add_u32_e32 v64, 0x80, v146
	s_waitcnt lgkmcnt(0)
	v_ashrrev_i32_e32 v65, 31, v64
	v_lshlrev_b64 v[66:67], 10, v[64:65]
	v_lshl_add_u64 v[66:67], v[66:67], 0, v[144:145]
	v_lshlrev_b64 v[70:71], 1, v[66:67]
	v_lshl_add_u64 v[72:73], s[84:85], 0, v[70:71]
	global_load_dwordx4 v[66:69], v[72:73], off
	v_lshl_add_u64 v[74:75], s[8:9], 0, v[70:71]
	v_or_b32_e32 v70, 0x100, v70
	global_load_dwordx4 v[228:231], v[72:73], off offset:256
	s_waitcnt vmcnt(0)
	v_lshlrev_b32_e32 v76, 16, v66
	v_and_b32_e32 v77, 0xffff0000, v66
	v_lshlrev_b32_e32 v66, 16, v67
	v_and_b32_e32 v67, 0xffff0000, v67
	v_lshlrev_b32_e32 v78, 16, v68
	v_and_b32_e32 v79, 0xffff0000, v68
	v_lshlrev_b32_e32 v68, 16, v69
	v_and_b32_e32 v69, 0xffff0000, v69
	v_pk_add_f32 v[62:63], v[62:63], v[66:67]
	v_pk_add_f32 v[60:61], v[60:61], v[76:77]
	v_pk_add_f32 v[66:67], v[58:59], v[68:69]
	v_pk_add_f32 v[68:69], v[56:57], v[78:79]
	v_cvt_pk_bf16_f32 v56, v60, v61
	v_cvt_pk_bf16_f32 v57, v62, v63
	v_cvt_pk_bf16_f32 v58, v68, v69
	v_cvt_pk_bf16_f32 v59, v66, v67
	global_store_dwordx4 v[74:75], v[56:59], off
	s_nop 1
	v_mul_f32_e32 v61, v61, v61
	v_mul_f32_e32 v63, v63, v63
	v_mul_f32_e32 v69, v69, v69
	v_mul_f32_e32 v67, v67, v67
	v_fmac_f32_e32 v61, v60, v60
	v_fmac_f32_e32 v63, v62, v62
	v_fmac_f32_e32 v69, v68, v68
	v_fmac_f32_e32 v67, v66, v66
	v_add_f32_e32 v60, v61, v63
	v_add_f32_e32 v61, v69, v67
	v_add_f32_e32 v66, v60, v61
	s_nop 0
	v_lshlrev_b32_e32 v60, 16, v228
	v_and_b32_e32 v61, 0xffff0000, v228
	v_lshlrev_b32_e32 v56, 16, v229
	v_and_b32_e32 v57, 0xffff0000, v229
	v_lshlrev_b32_e32 v62, 16, v230
	v_and_b32_e32 v63, 0xffff0000, v230
	v_lshlrev_b32_e32 v58, 16, v231
	v_and_b32_e32 v59, 0xffff0000, v231
	v_pk_add_f32 v[54:55], v[54:55], v[56:57]
	v_pk_add_f32 v[52:53], v[52:53], v[60:61]
	v_pk_add_f32 v[56:57], v[50:51], v[58:59]
	v_pk_add_f32 v[48:49], v[48:49], v[62:63]
	v_mul_f32_e32 v50, v53, v53
	v_mul_f32_e32 v51, v55, v55
	v_mul_f32_e32 v58, v49, v49
	v_mul_f32_e32 v59, v57, v57
	v_fmac_f32_e32 v50, v52, v52
	v_fmac_f32_e32 v51, v54, v54
	v_fmac_f32_e32 v58, v48, v48
	v_fmac_f32_e32 v59, v56, v56
	v_add_f32_e32 v50, v50, v51
	v_add_f32_e32 v51, v58, v59
	v_add_f32_e32 v50, v50, v51
	v_add_f32_e32 v58, v66, v50
	ds_bpermute_b32 v59, v120, v58
	v_cvt_pk_bf16_f32 v50, v52, v53
	v_cvt_pk_bf16_f32 v52, v48, v49
	v_cvt_pk_bf16_f32 v51, v54, v55
	v_cvt_pk_bf16_f32 v53, v56, v57
	s_waitcnt lgkmcnt(0)
	v_add_f32_e32 v48, v58, v59
	ds_bpermute_b32 v49, v114, v48
	v_lshl_add_u64 v[54:55], s[8:9], 0, v[70:71]
	global_store_dwordx4 v[54:55], v[50:53], off
	s_and_saveexec_b64 s[22:23], s[2:3]
	s_cbranch_execz .LBB0_1026
	v_lshl_add_u64 v[50:51], v[64:65], 2, s[0:1]
	s_waitcnt lgkmcnt(0)
	v_add_f32_e32 v48, v48, v49
	global_atomic_add_f32 v[50:51], v48, off
.LBB0_1026:
	s_or_b64 exec, exec, s[22:23]
	v_add_u32_e32 v48, 0x90, v146
	s_waitcnt lgkmcnt(0)
	v_ashrrev_i32_e32 v49, 31, v48
	v_lshlrev_b64 v[50:51], 10, v[48:49]
	v_lshl_add_u64 v[50:51], v[50:51], 0, v[144:145]
	v_lshlrev_b64 v[54:55], 1, v[50:51]
	v_lshl_add_u64 v[56:57], s[84:85], 0, v[54:55]
	global_load_dwordx4 v[50:53], v[56:57], off
	v_lshl_add_u64 v[58:59], s[8:9], 0, v[54:55]
	v_or_b32_e32 v54, 0x100, v54
	global_load_dwordx4 v[232:235], v[56:57], off offset:256
	s_waitcnt vmcnt(0)
	v_lshlrev_b32_e32 v60, 16, v50
	v_and_b32_e32 v61, 0xffff0000, v50
	v_lshlrev_b32_e32 v50, 16, v51
	v_and_b32_e32 v51, 0xffff0000, v51
	v_lshlrev_b32_e32 v62, 16, v52
	v_and_b32_e32 v63, 0xffff0000, v52
	v_lshlrev_b32_e32 v52, 16, v53
	v_and_b32_e32 v53, 0xffff0000, v53
	v_pk_add_f32 v[46:47], v[46:47], v[50:51]
	v_pk_add_f32 v[44:45], v[44:45], v[60:61]
	v_pk_add_f32 v[50:51], v[42:43], v[52:53]
	v_pk_add_f32 v[52:53], v[40:41], v[62:63]
	v_cvt_pk_bf16_f32 v40, v44, v45
	v_cvt_pk_bf16_f32 v41, v46, v47
	v_cvt_pk_bf16_f32 v42, v52, v53
	v_cvt_pk_bf16_f32 v43, v50, v51
	global_store_dwordx4 v[58:59], v[40:43], off
	s_nop 1
	v_mul_f32_e32 v45, v45, v45
	v_mul_f32_e32 v47, v47, v47
	v_mul_f32_e32 v53, v53, v53
	v_mul_f32_e32 v51, v51, v51
	v_fmac_f32_e32 v45, v44, v44
	v_fmac_f32_e32 v47, v46, v46
	v_fmac_f32_e32 v53, v52, v52
	v_fmac_f32_e32 v51, v50, v50
	v_add_f32_e32 v44, v45, v47
	v_add_f32_e32 v45, v53, v51
	v_add_f32_e32 v50, v44, v45
	s_nop 0
	v_lshlrev_b32_e32 v44, 16, v232
	v_and_b32_e32 v45, 0xffff0000, v232
	v_lshlrev_b32_e32 v40, 16, v233
	v_and_b32_e32 v41, 0xffff0000, v233
	v_lshlrev_b32_e32 v46, 16, v234
	v_and_b32_e32 v47, 0xffff0000, v234
	v_lshlrev_b32_e32 v42, 16, v235
	v_and_b32_e32 v43, 0xffff0000, v235
	v_pk_add_f32 v[38:39], v[38:39], v[40:41]
	v_pk_add_f32 v[36:37], v[36:37], v[44:45]
	v_pk_add_f32 v[40:41], v[34:35], v[42:43]
	v_pk_add_f32 v[32:33], v[32:33], v[46:47]
	v_mul_f32_e32 v34, v37, v37
	v_mul_f32_e32 v35, v39, v39
	v_mul_f32_e32 v42, v33, v33
	v_mul_f32_e32 v43, v41, v41
	v_fmac_f32_e32 v34, v36, v36
	v_fmac_f32_e32 v35, v38, v38
	v_fmac_f32_e32 v42, v32, v32
	v_fmac_f32_e32 v43, v40, v40
	v_add_f32_e32 v34, v34, v35
	v_add_f32_e32 v35, v42, v43
	v_add_f32_e32 v34, v34, v35
	v_add_f32_e32 v42, v50, v34
	ds_bpermute_b32 v43, v120, v42
	v_cvt_pk_bf16_f32 v34, v36, v37
	v_cvt_pk_bf16_f32 v36, v32, v33
	v_cvt_pk_bf16_f32 v35, v38, v39
	v_cvt_pk_bf16_f32 v37, v40, v41
	s_waitcnt lgkmcnt(0)
	v_add_f32_e32 v32, v42, v43
	ds_bpermute_b32 v33, v114, v32
	v_lshl_add_u64 v[38:39], s[8:9], 0, v[54:55]
	global_store_dwordx4 v[38:39], v[34:37], off
	s_and_saveexec_b64 s[22:23], s[2:3]
	s_cbranch_execz .LBB0_1028
	v_lshl_add_u64 v[34:35], v[48:49], 2, s[0:1]
	s_waitcnt lgkmcnt(0)
	v_add_f32_e32 v32, v32, v33
	global_atomic_add_f32 v[34:35], v32, off
; __device__ __forceinline__ unsigned cvt_pk_bf16(float lo, float hi) { f32x2_t v = {lo, hi}; bf16x2_t b = __builtin_convertvector(v, bf16x2_t); return __builtin_bit_cast(unsigned, b); }
;     __device__ __forceinline__ void operator()(const f32x4 (&acc)[2][2][4][2], const Unit& u, int wr, int wc, int fr, int fq) const {
;     ...
;             for (int m = 0; m < 4; ++m) {
;                 const int row = u.pm * BM + ai * HALF + wr * 64 + m * 16 + fr; float ss = 0.f; const float bsc = brow ? brow[row] : 1.0f;
; #pragma unroll
;                 for (int bj = 0; bj < 2; ++bj) { const size_t off = (size_t)row * 1024 + col0 + bj * HALF;
;                     f32x4 b0, b1;
;                     if (basef) { b0 = *(const f32x4*)(basef + off); b1 = *(const f32x4*)(basef + off + 4); }
;                     else { const u32x4 r = *(const u32x4*)(baseh + off);
;                         b0 = (f32x4){__uint_as_float(r.x << 16), __uint_as_float(r.x & 0xffff0000u), __uint_as_float(r.y << 16), __uint_as_float(r.y & 0xffff0000u)} * bsc;
;                         b1 = (f32x4){__uint_as_float(r.z << 16), __uint_as_float(r.z & 0xffff0000u), __uint_as_float(r.w << 16), __uint_as_float(r.w & 0xffff0000u)} * bsc; }
;                     const f32x4 o0 = b0 + acc[ai][bj][m][0] * scale, o1 = b1 + acc[ai][bj][m][1] * scale;
;                     if (out) { __builtin_nontemporal_store(o0, (f32x4*)(out + off)); __builtin_nontemporal_store(o1, (f32x4*)(out + off + 4)); }
;                     if (hb) { u32x4 w; w.x = cvt_pk_bf16(o0[0], o0[1]); w.y = cvt_pk_bf16(o0[2], o0[3]); w.z = cvt_pk_bf16(o1[0], o1[1]); w.w = cvt_pk_bf16(o1[2], o1[3]); *(u32x4*)(hb + off) = w;
;                         ss += ((o0[0] * o0[0] + o0[1] * o0[1]) + (o0[2] * o0[2] + o0[3] * o0[3])) + ((o1[0] * o1[0] + o1[1] * o1[1]) + (o1[2] * o1[2] + o1[3] * o1[3])); } }
;                 if (hb) { ss += __shfl_xor(ss, 16); ss += __shfl_xor(ss, 32); if (fq == 0) atomicAdd(rowss + row, ss); }
.LBB0_1028:
	s_or_b64 exec, exec, s[22:23]
	v_add_u32_e32 v32, 0xa0, v146
	s_waitcnt lgkmcnt(0)
	v_ashrrev_i32_e32 v33, 31, v32
	v_lshlrev_b64 v[34:35], 10, v[32:33]
	v_lshl_add_u64 v[34:35], v[34:35], 0, v[144:145]
	v_lshlrev_b64 v[38:39], 1, v[34:35]
	v_lshl_add_u64 v[40:41], s[84:85], 0, v[38:39]
	global_load_dwordx4 v[34:37], v[40:41], off
	v_lshl_add_u64 v[42:43], s[8:9], 0, v[38:39]
	v_or_b32_e32 v38, 0x100, v38
	global_load_dwordx4 v[228:231], v[40:41], off offset:256
	s_waitcnt vmcnt(0)
	v_lshlrev_b32_e32 v44, 16, v34
	v_and_b32_e32 v45, 0xffff0000, v34
	v_lshlrev_b32_e32 v34, 16, v35
	v_and_b32_e32 v35, 0xffff0000, v35
	v_lshlrev_b32_e32 v46, 16, v36
	v_and_b32_e32 v47, 0xffff0000, v36
	v_lshlrev_b32_e32 v36, 16, v37
	v_and_b32_e32 v37, 0xffff0000, v37
	v_pk_add_f32 v[30:31], v[30:31], v[34:35]
	v_pk_add_f32 v[28:29], v[28:29], v[44:45]
	v_pk_add_f32 v[34:35], v[26:27], v[36:37]
	v_pk_add_f32 v[36:37], v[24:25], v[46:47]
	v_cvt_pk_bf16_f32 v24, v28, v29
	v_cvt_pk_bf16_f32 v25, v30, v31
	v_cvt_pk_bf16_f32 v26, v36, v37
	v_cvt_pk_bf16_f32 v27, v34, v35
	global_store_dwordx4 v[42:43], v[24:27], off
	s_nop 1
	v_mul_f32_e32 v29, v29, v29
	v_mul_f32_e32 v31, v31, v31
	v_mul_f32_e32 v37, v37, v37
	v_mul_f32_e32 v35, v35, v35
	v_fmac_f32_e32 v29, v28, v28
	v_fmac_f32_e32 v31, v30, v30
	v_fmac_f32_e32 v37, v36, v36
	v_fmac_f32_e32 v35, v34, v34
	v_add_f32_e32 v28, v29, v31
	v_add_f32_e32 v29, v37, v35
	v_add_f32_e32 v34, v28, v29
	s_nop 0
	v_lshlrev_b32_e32 v28, 16, v228
	v_and_b32_e32 v29, 0xffff0000, v228
	v_lshlrev_b32_e32 v24, 16, v229
	v_and_b32_e32 v25, 0xffff0000, v229
	v_lshlrev_b32_e32 v30, 16, v230
	v_and_b32_e32 v31, 0xffff0000, v230
	v_lshlrev_b32_e32 v26, 16, v231
	v_and_b32_e32 v27, 0xffff0000, v231
	v_pk_add_f32 v[22:23], v[22:23], v[24:25]
	v_pk_add_f32 v[20:21], v[20:21], v[28:29]
	v_pk_add_f32 v[24:25], v[18:19], v[26:27]
	v_pk_add_f32 v[16:17], v[16:17], v[30:31]
	v_mul_f32_e32 v18, v21, v21
	v_mul_f32_e32 v19, v23, v23
	v_mul_f32_e32 v26, v17, v17
	v_mul_f32_e32 v27, v25, v25
	v_fmac_f32_e32 v18, v20, v20
	v_fmac_f32_e32 v19, v22, v22
	v_fmac_f32_e32 v26, v16, v16
	v_fmac_f32_e32 v27, v24, v24
	v_add_f32_e32 v18, v18, v19
	v_add_f32_e32 v19, v26, v27
	v_add_f32_e32 v18, v18, v19
	v_add_f32_e32 v26, v34, v18
	ds_bpermute_b32 v27, v120, v26
	v_cvt_pk_bf16_f32 v18, v20, v21
	v_cvt_pk_bf16_f32 v20, v16, v17
	v_cvt_pk_bf16_f32 v19, v22, v23
	v_cvt_pk_bf16_f32 v21, v24, v25
	s_waitcnt lgkmcnt(0)
	v_add_f32_e32 v16, v26, v27
	ds_bpermute_b32 v17, v114, v16
	v_lshl_add_u64 v[22:23], s[8:9], 0, v[38:39]
	global_store_dwordx4 v[22:23], v[18:21], off
	s_and_saveexec_b64 s[22:23], s[2:3]
	s_cbranch_execz .LBB0_1030
	v_lshl_add_u64 v[18:19], v[32:33], 2, s[0:1]
	s_waitcnt lgkmcnt(0)
	v_add_f32_e32 v16, v16, v17
	global_atomic_add_f32 v[18:19], v16, off
.LBB0_1030:
	s_or_b64 exec, exec, s[22:23]
	v_add_u32_e32 v16, 0xb0, v146
	s_waitcnt lgkmcnt(0)
	v_ashrrev_i32_e32 v17, 31, v16
	v_lshlrev_b64 v[18:19], 10, v[16:17]
	v_lshl_add_u64 v[18:19], v[18:19], 0, v[144:145]
	v_lshlrev_b64 v[22:23], 1, v[18:19]
	v_lshl_add_u64 v[24:25], s[84:85], 0, v[22:23]
	global_load_dwordx4 v[18:21], v[24:25], off
	v_lshl_add_u64 v[26:27], s[8:9], 0, v[22:23]
	v_or_b32_e32 v22, 0x100, v22
	global_load_dwordx4 v[232:235], v[24:25], off offset:256
	s_waitcnt vmcnt(0)
	v_lshlrev_b32_e32 v28, 16, v18
	v_and_b32_e32 v29, 0xffff0000, v18
	v_lshlrev_b32_e32 v18, 16, v19
	v_and_b32_e32 v19, 0xffff0000, v19
	v_lshlrev_b32_e32 v30, 16, v20
	v_and_b32_e32 v31, 0xffff0000, v20
	v_lshlrev_b32_e32 v20, 16, v21
	v_and_b32_e32 v21, 0xffff0000, v21
	v_pk_add_f32 v[14:15], v[14:15], v[18:19]
	v_pk_add_f32 v[12:13], v[12:13], v[28:29]
	v_pk_add_f32 v[18:19], v[10:11], v[20:21]
	v_pk_add_f32 v[20:21], v[8:9], v[30:31]
	v_cvt_pk_bf16_f32 v8, v12, v13
	v_cvt_pk_bf16_f32 v9, v14, v15
	v_cvt_pk_bf16_f32 v10, v20, v21
	v_cvt_pk_bf16_f32 v11, v18, v19
	global_store_dwordx4 v[26:27], v[8:11], off
	s_nop 1
	v_mul_f32_e32 v13, v13, v13
	v_mul_f32_e32 v15, v15, v15
	v_mul_f32_e32 v21, v21, v21
	v_mul_f32_e32 v19, v19, v19
	v_fmac_f32_e32 v13, v12, v12
	v_fmac_f32_e32 v15, v14, v14
	v_fmac_f32_e32 v21, v20, v20
	v_fmac_f32_e32 v19, v18, v18
	v_add_f32_e32 v12, v13, v15
	v_add_f32_e32 v13, v21, v19
	v_add_f32_e32 v18, v12, v13
	s_nop 0
	v_lshlrev_b32_e32 v12, 16, v232
	v_and_b32_e32 v13, 0xffff0000, v232
	v_lshlrev_b32_e32 v8, 16, v233
	v_and_b32_e32 v9, 0xffff0000, v233
	v_lshlrev_b32_e32 v14, 16, v234
	v_and_b32_e32 v15, 0xffff0000, v234
	v_lshlrev_b32_e32 v10, 16, v235
	v_and_b32_e32 v11, 0xffff0000, v235
	v_pk_add_f32 v[6:7], v[6:7], v[8:9]
	v_pk_add_f32 v[4:5], v[4:5], v[12:13]
	v_pk_add_f32 v[8:9], v[2:3], v[10:11]
	v_pk_add_f32 v[0:1], v[0:1], v[14:15]
	v_mul_f32_e32 v2, v5, v5
	v_mul_f32_e32 v3, v7, v7
	v_mul_f32_e32 v10, v1, v1
	v_mul_f32_e32 v11, v9, v9
	v_fmac_f32_e32 v2, v4, v4
	v_fmac_f32_e32 v3, v6, v6
	v_fmac_f32_e32 v10, v0, v0
	v_fmac_f32_e32 v11, v8, v8
	v_add_f32_e32 v2, v2, v3
	v_add_f32_e32 v3, v10, v11
	v_add_f32_e32 v2, v2, v3
	v_add_f32_e32 v10, v18, v2
	ds_bpermute_b32 v11, v120, v10
	v_cvt_pk_bf16_f32 v2, v4, v5
	v_cvt_pk_bf16_f32 v4, v0, v1
	v_cvt_pk_bf16_f32 v3, v6, v7
	v_cvt_pk_bf16_f32 v5, v8, v9
	s_waitcnt lgkmcnt(0)
	v_add_f32_e32 v0, v10, v11
	ds_bpermute_b32 v1, v114, v0
	v_lshl_add_u64 v[6:7], s[8:9], 0, v[22:23]
	global_store_dwordx4 v[6:7], v[2:5], off
	s_and_saveexec_b64 s[22:23], s[2:3]
	s_cbranch_execz .LBB0_1032
	v_lshl_add_u64 v[2:3], v[16:17], 2, s[0:1]
	s_waitcnt lgkmcnt(0)
	v_add_f32_e32 v0, v0, v1
	global_atomic_add_f32 v[2:3], v0, off
